# prompt attention: odd half-step also issues the next tile's staging loads before QK^T (its QK^T/softmax temporaries renamed off the staging registers; wait counts re-derived +5)
# speedup vs baseline: 1.0062x; 1.0026x over previous
; __device__ __forceinline__ void finishSM(f32x16& p0, f32x16& p1, float alpha, float& l_reg, bf16x8& pa0, bf16x8& pa1, bf16x8& pa2, bf16x8& pa3) {
;     for (int r = 0; r < 16; ++r) p1[r] = __builtin_amdgcn_exp2f(p1[r]);
;     float ps = 0; for (int r = 0; r < 16; ++r) ps += p0[r]; for (int r = 0; r < 16; ++r) ps += p1[r];
;     { auto rr = __builtin_amdgcn_permlane32_swap(__float_as_uint(ps), __float_as_uint(ps), false, false);
;       ps = __uint_as_float(rr[0]) + __uint_as_float(rr[1]); }
;     l_reg = l_reg * alpha + ps;
;     ...
;     PK4(p0, 0, pa0); PK4(p0, 8, pa1); PK4(p1, 0, pa2); PK4(p1, 8, pa3);
;     ...
; }
; template <int KB, bool SK>
; __device__ __forceinline__ void qkt(f32x16& p0, f32x16& p1, const char* K_lds, const float* B_lds, int r32, int hi, const bf16x8* qr, bool act) {
;     if (SK && !act) { const float NEG = -__builtin_inff();
; #pragma unroll
;         for (int r = 0; r < 16; ++r) { p0[r] = NEG; p1[r] = NEG; } return; }
;     ...
;     p0 = f32x16{}; p1 = f32x16{};
;     ...
;     p0 = *(const f32x16*)(B_lds + KB * 64 + hi * 32); p1 = *(const f32x16*)(B_lds + KB * 64 + hi * 32 + 16);
;     ...
;     const char* kb[4];
; #pragma unroll
;     for (int dd = 0; dd < 4; ++dd) kb[dd] = K_lds + KB * SHM_K + KSWZ(r32, (dd * 16 + hi * 8) * 2);
; #pragma unroll
;     for (int d0 = 0; d0 < 8; ++d0) { const char* a = kb[d0 & 3] + (d0 >> 2) * 128;
;         bf16x8 b0 = *reinterpret_cast<const bf16x8*>(a);
;         bf16x8 b1 = *reinterpret_cast<const bf16x8*>(a + 32 * 256);
;         p0 = __builtin_amdgcn_mfma_f32_32x32x16_bf16(b0, qr[d0], p0, 0, 0, 0);
;         p1 = __builtin_amdgcn_mfma_f32_32x32x16_bf16(b1, qr[d0], p1, 0, 0, 0); }
; }
.LBB0_1247:
	v_add_u32_e32 v200, v230, v219
	v_add_u32_e32 v248, s68, v200
	v_add_u32_e32 v200, 1, v248
	v_lshl_add_u64 v[2:3], v[200:201], 2, s[66:67]
	v_mov_b32_e32 v15, v1
	v_add_u32_e32 v200, 0x10000, v14
	v_lshlrev_b64 v[10:11], 1, v[14:15]
	v_lshlrev_b64 v[12:13], 1, v[200:201]
	global_load_dword v246, v[2:3], off
	v_lshl_add_u64 v[2:3], s[64:65], 0, v[10:11]
	v_lshl_add_u64 v[6:7], s[64:65], 0, v[12:13]
	v_lshl_add_u64 v[10:11], s[62:63], 0, v[10:11]
	global_load_dwordx4 v[2:5], v[2:3], off
	s_nop 0
	global_load_dwordx4 v[6:9], v[6:7], off
	v_lshl_add_u64 v[210:211], s[62:63], 0, v[12:13]
	global_load_dwordx4 v[10:13], v[10:11], off
	s_nop 0
	global_load_dwordx4 v[210:213], v[210:211], off
	v_add_u32_e32 v0, 0x10900, v236
	ds_read_b128 v[100:103], v0
	ds_read_b128 v[104:107], v0 offset:16
	ds_read_b128 v[108:111], v0 offset:32
	s_waitcnt vmcnt(7)
	ds_read_b128 v[112:115], v0 offset:48
	ds_read_b128 v[96:99], v0 offset:112
	ds_read_b128 v[92:95], v0 offset:96
	ds_read_b128 v[88:91], v0 offset:80
	ds_read_b128 v[84:87], v0 offset:64
	ds_read_b128 v[202:205], v235 offset:49152
	ds_read_b128 v[206:209], v235 offset:57344
	v_add_f32_e32 v80, 0, v191
	v_add_f32_e32 v80, v193, v80
	v_add_f32_e32 v80, v189, v80
	s_waitcnt lgkmcnt(1)
	v_mfma_f32_32x32x16_bf16 v[100:115], v[202:205], v[172:175], v[100:115]
	v_add_f32_e32 v80, v192, v80
	v_add_f32_e32 v80, v188, v80
	v_add_f32_e32 v80, v190, v80
	v_add_f32_e32 v80, v186, v80
	v_add_f32_e32 v80, v187, v80
	v_add_f32_e32 v80, v182, v80
	v_add_f32_e32 v80, v185, v80
	s_waitcnt lgkmcnt(0)
	v_mfma_f32_32x32x16_bf16 v[84:99], v[206:209], v[172:175], v[84:99]
	ds_read_b128 v[202:205], v234 offset:49152
	ds_read_b128 v[206:209], v234 offset:57344
	v_add_f32_e32 v80, v179, v80
	v_add_f32_e32 v80, v183, v80
	v_exp_f32_e32 v0, v142
	v_add_f32_e32 v80, v177, v80
	v_add_f32_e32 v80, v184, v80
	v_add_f32_e32 v80, v178, v80
	s_waitcnt lgkmcnt(1)
	v_mfma_f32_32x32x16_bf16 v[100:115], v[202:205], v[168:171], v[100:115]
	v_add_f32_e32 v80, v181, v80
	v_add_f32_e32 v80, v0, v80
	v_exp_f32_e32 v194, v135
	v_exp_f32_e32 v195, v132
	v_exp_f32_e32 v196, v133
	v_exp_f32_e32 v197, v130
	v_exp_f32_e32 v198, v131
	s_waitcnt lgkmcnt(0)
	v_mfma_f32_32x32x16_bf16 v[84:99], v[206:209], v[168:171], v[84:99]
	ds_read_b128 v[202:205], v233 offset:49152
	ds_read_b128 v[206:209], v233 offset:57344
	v_exp_f32_e32 v127, v128
	v_exp_f32_e32 v128, v129
	s_sub_i32 s4, s68, 63
	s_waitcnt lgkmcnt(1)
	v_mfma_f32_32x32x16_bf16 v[100:115], v[202:205], v[164:167], v[100:115]
	s_waitcnt lgkmcnt(0)
	v_mfma_f32_32x32x16_bf16 v[84:99], v[206:209], v[164:167], v[84:99]
	ds_read_b128 v[202:205], v232 offset:49152
	ds_read_b128 v[206:209], v232 offset:57344
	s_waitcnt lgkmcnt(1)
	v_mfma_f32_32x32x16_bf16 v[100:115], v[202:205], v[160:163], v[100:115]
	s_waitcnt lgkmcnt(0)
	v_mfma_f32_32x32x16_bf16 v[84:99], v[206:209], v[160:163], v[84:99]
	ds_read_b128 v[202:205], v235 offset:49280
	ds_read_b128 v[206:209], v235 offset:57472
	s_waitcnt lgkmcnt(1)
	v_mfma_f32_32x32x16_bf16 v[100:115], v[202:205], v[156:159], v[100:115]
	s_waitcnt lgkmcnt(0)
	v_mfma_f32_32x32x16_bf16 v[84:99], v[206:209], v[156:159], v[84:99]
	ds_read_b128 v[202:205], v234 offset:49280
	ds_read_b128 v[206:209], v234 offset:57472
	s_waitcnt lgkmcnt(1)
	v_mfma_f32_32x32x16_bf16 v[100:115], v[202:205], v[152:155], v[100:115]
	s_waitcnt lgkmcnt(0)
	v_mfma_f32_32x32x16_bf16 v[84:99], v[206:209], v[152:155], v[84:99]
	ds_read_b128 v[202:205], v233 offset:49280
	ds_read_b128 v[206:209], v233 offset:57472
	s_waitcnt lgkmcnt(1)
	v_mfma_f32_32x32x16_bf16 v[100:115], v[202:205], v[148:151], v[100:115]
	s_waitcnt lgkmcnt(0)
	v_mfma_f32_32x32x16_bf16 v[84:99], v[206:209], v[148:151], v[84:99]
	ds_read_b128 v[202:205], v232 offset:49280
	ds_read_b128 v[206:209], v232 offset:57472
	s_waitcnt lgkmcnt(1)
	v_mfma_f32_32x32x16_bf16 v[100:115], v[202:205], v[144:147], v[100:115]
	v_exp_f32_e32 v202, v143
	v_exp_f32_e32 v203, v140
	v_exp_f32_e32 v204, v141
	v_exp_f32_e32 v205, v138
	v_add_f32_e32 v80, v202, v80
	v_add_f32_e32 v80, v203, v80
	v_add_f32_e32 v80, v204, v80
	s_waitcnt lgkmcnt(0)
	v_mfma_f32_32x32x16_bf16 v[84:99], v[206:209], v[144:147], v[84:99]
	v_exp_f32_e32 v206, v139
	v_exp_f32_e32 v207, v136
	v_exp_f32_e32 v208, v137
	v_exp_f32_e32 v209, v134
	v_add_f32_e32 v80, v205, v80
	v_add_f32_e32 v80, v206, v80
	v_add_f32_e32 v80, v207, v80
	v_add_f32_e32 v80, v208, v80
	v_add_f32_e32 v80, v209, v80
	v_add_f32_e32 v80, v194, v80
	v_add_f32_e32 v80, v195, v80
	v_add_f32_e32 v80, v196, v80
	v_add_f32_e32 v80, v197, v80
	v_add_f32_e32 v80, v198, v80
	v_add_f32_e32 v80, v127, v80
	v_add_f32_e32 v244, v128, v80
	v_mov_b32_e32 v245, v244
	s_nop 1
	v_permlane32_swap_b32_e32 v244, v245
	v_cvt_pk_bf16_f32 v80, v191, v193
	v_cvt_pk_bf16_f32 v81, v189, v192
	v_cvt_pk_bf16_f32 v82, v188, v190
	v_cvt_pk_bf16_f32 v83, v186, v187
	s_waitcnt vmcnt(6)
	v_cvt_pk_bf16_f32 v116, v182, v185
	v_cvt_pk_bf16_f32 v117, v179, v183
	v_cvt_pk_bf16_f32 v118, v177, v184
	v_cvt_pk_bf16_f32 v119, v178, v181
	s_waitcnt vmcnt(5)
	v_cvt_pk_bf16_f32 v120, v0, v202
	v_cvt_pk_bf16_f32 v121, v203, v204
	v_cvt_pk_bf16_f32 v122, v205, v206
	v_cvt_pk_bf16_f32 v123, v207, v208
	v_cvt_pk_bf16_f32 v124, v209, v194
	v_cvt_pk_bf16_f32 v125, v195, v196
	v_cvt_pk_bf16_f32 v126, v197, v198
	v_cvt_pk_bf16_f32 v127, v127, v128
	v_permlane32_swap_b32_e32 v80, v82
	v_permlane32_swap_b32_e32 v81, v83
	v_permlane32_swap_b32_e32 v116, v118
	v_permlane32_swap_b32_e32 v117, v119
	v_permlane32_swap_b32_e32 v120, v122
	v_permlane32_swap_b32_e32 v121, v123
	v_permlane32_swap_b32_e32 v124, v126
	v_permlane32_swap_b32_e32 v125, v127
	ds_read_b64_tr_b16 v[128:129], v227 offset:0
	ds_read_b64_tr_b16 v[130:131], v227 offset:0x800
	ds_read_b64_tr_b16 v[132:133], v227 offset:0x1000
	ds_read_b64_tr_b16 v[134:135], v227 offset:0x1800
	ds_read_b64_tr_b16 v[136:137], v227 offset:0x2000
	ds_read_b64_tr_b16 v[138:139], v227 offset:0x2800
	ds_read_b64_tr_b16 v[140:141], v227 offset:0x3000
	ds_read_b64_tr_b16 v[142:143], v227 offset:0x3800
	s_waitcnt lgkmcnt(0)
; __device__ __forceinline__ void mask_tile(f32x16& p0, f32x16& p1, int dq, unsigned W) {
;     const float NEG = -__builtin_inff();
; #pragma unroll
;     for (int r = 0; r < 16; ++r) {
;         const int c = (r & 3) + 8 * (r >> 2);
;         if ((unsigned)(dq - c) >= W) p0[r] = NEG;
;         if ((unsigned)(dq - c - 32) >= W) p1[r] = NEG;
;     }
; }
; template <int VB, bool SK>
; __device__ __forceinline__ void pv_tile(f32x16* o, int vb0, bf16x8 pa0, bf16x8 pa1, bf16x8 pa2, bf16x8 pa3, bool act) {
;     if (SK && !act) return;
;     ...
;     PV_D0(0); PV_D0(1); PV_D0(2); PV_D0(3);
	s_nop 0
	v_mfma_f32_32x32x16_bf16 v[64:79], v[80:83], v[128:131], v[64:79]
	ds_read_b64_tr_b16 v[128:129], v227 offset:0x200
	ds_read_b64_tr_b16 v[130:131], v227 offset:0xa00
	v_mfma_f32_32x32x16_bf16 v[64:79], v[116:119], v[132:135], v[64:79]
	ds_read_b64_tr_b16 v[132:133], v227 offset:0x1200
	ds_read_b64_tr_b16 v[134:135], v227 offset:0x1a00
	v_mfma_f32_32x32x16_bf16 v[64:79], v[120:123], v[136:139], v[64:79]
	ds_read_b64_tr_b16 v[136:137], v227 offset:0x2200
	ds_read_b64_tr_b16 v[138:139], v227 offset:0x2a00
	v_mfma_f32_32x32x16_bf16 v[64:79], v[124:127], v[140:143], v[64:79]
	ds_read_b64_tr_b16 v[140:141], v227 offset:0x3200
	ds_read_b64_tr_b16 v[142:143], v227 offset:0x3a00
	s_waitcnt lgkmcnt(0)
	v_mfma_f32_32x32x16_bf16 v[48:63], v[80:83], v[128:131], v[48:63]
	ds_read_b64_tr_b16 v[128:129], v227 offset:0x400
	ds_read_b64_tr_b16 v[130:131], v227 offset:0xc00
	v_mfma_f32_32x32x16_bf16 v[48:63], v[116:119], v[132:135], v[48:63]
	ds_read_b64_tr_b16 v[132:133], v227 offset:0x1400
	ds_read_b64_tr_b16 v[134:135], v227 offset:0x1c00
	v_mfma_f32_32x32x16_bf16 v[48:63], v[120:123], v[136:139], v[48:63]
	ds_read_b64_tr_b16 v[136:137], v227 offset:0x2400
	ds_read_b64_tr_b16 v[138:139], v227 offset:0x2c00
	v_mfma_f32_32x32x16_bf16 v[48:63], v[124:127], v[140:143], v[48:63]
	ds_read_b64_tr_b16 v[140:141], v227 offset:0x3400
	ds_read_b64_tr_b16 v[142:143], v227 offset:0x3c00
	s_waitcnt lgkmcnt(0)
	v_mfma_f32_32x32x16_bf16 v[32:47], v[80:83], v[128:131], v[32:47]
	ds_read_b64_tr_b16 v[128:129], v227 offset:0x600
	ds_read_b64_tr_b16 v[130:131], v227 offset:0xe00
	v_mfma_f32_32x32x16_bf16 v[32:47], v[116:119], v[132:135], v[32:47]
	ds_read_b64_tr_b16 v[132:133], v227 offset:0x1600
	ds_read_b64_tr_b16 v[134:135], v227 offset:0x1e00
	v_mfma_f32_32x32x16_bf16 v[32:47], v[120:123], v[136:139], v[32:47]
	ds_read_b64_tr_b16 v[136:137], v227 offset:0x2600
	ds_read_b64_tr_b16 v[138:139], v227 offset:0x2e00
	v_mfma_f32_32x32x16_bf16 v[32:47], v[124:127], v[140:143], v[32:47]
	ds_read_b64_tr_b16 v[140:141], v227 offset:0x3600
	ds_read_b64_tr_b16 v[142:143], v227 offset:0x3e00
	s_waitcnt lgkmcnt(0)
	v_mfma_f32_32x32x16_bf16 v[16:31], v[80:83], v[128:131], v[16:31]
	s_cmp_le_i32 s68, s57
	s_cselect_b64 s[28:29], -1, 0
	s_cmp_gt_i32 s4, s58
	s_cselect_b64 s[4:5], -1, 0
	s_and_b64 s[4:5], s[28:29], s[4:5]
	s_and_b64 vcc, exec, s[4:5]
	v_mfma_f32_32x32x16_bf16 v[16:31], v[116:119], v[132:135], v[16:31]
	v_mfma_f32_32x32x16_bf16 v[16:31], v[120:123], v[136:139], v[16:31]
	v_mfma_f32_32x32x16_bf16 v[16:31], v[124:127], v[140:143], v[16:31]
	s_cbranch_vccnz .LBB0_1249
	v_add_u32_e32 v0, 0x107b, v243
	v_cmp_gt_u32_e32 vcc, s81, v0
	v_add_u32_e32 v0, 0x5b, v243
	s_nop 0
	v_cndmask_b32_e32 v100, v216, v100, vcc
	v_cmp_lt_u32_e32 vcc, s82, v0
	v_add_u32_e32 v0, 0x7a, v243
	s_nop 0
	v_cndmask_b32_e32 v84, v216, v84, vcc
	v_cmp_lt_u32_e32 vcc, s82, v0
	v_add_u32_e32 v0, 0x5a, v243
	s_nop 0
	v_cndmask_b32_e32 v101, v216, v101, vcc
	v_cmp_lt_u32_e32 vcc, s82, v0
	v_add_u32_e32 v0, 0x79, v243
	s_nop 0
	v_cndmask_b32_e32 v85, v216, v85, vcc
	v_cmp_lt_u32_e32 vcc, s82, v0
	v_add_u32_e32 v0, 0x59, v243
	s_nop 0
	v_cndmask_b32_e32 v102, v216, v102, vcc
	v_cmp_lt_u32_e32 vcc, s82, v0
	v_add_u32_e32 v0, 0x78, v243
	s_nop 0
	v_cndmask_b32_e32 v86, v216, v86, vcc
	v_cmp_lt_u32_e32 vcc, s82, v0
	v_add_u32_e32 v0, 0x58, v243
	s_nop 0
	v_cndmask_b32_e32 v103, v216, v103, vcc
	v_cmp_lt_u32_e32 vcc, s82, v0
	v_add_u32_e32 v0, 0x73, v243
	s_nop 0
	v_cndmask_b32_e32 v87, v216, v87, vcc
	v_cmp_lt_u32_e32 vcc, s82, v0
	v_add_u32_e32 v0, 0x53, v243
	s_nop 0
	v_cndmask_b32_e32 v104, v216, v104, vcc
	v_cmp_lt_u32_e32 vcc, s82, v0
	v_add_u32_e32 v0, 0x72, v243
	s_nop 0
	v_cndmask_b32_e32 v88, v216, v88, vcc
	v_cmp_lt_u32_e32 vcc, s82, v0
	v_add_u32_e32 v0, 0x52, v243
	s_nop 0
	v_cndmask_b32_e32 v105, v216, v105, vcc
	v_cmp_lt_u32_e32 vcc, s82, v0
	v_add_u32_e32 v0, 0x71, v243
	s_nop 0
	v_cndmask_b32_e32 v89, v216, v89, vcc
	v_cmp_lt_u32_e32 vcc, s82, v0
	v_add_u32_e32 v0, 0x51, v243
	s_nop 0
	v_cndmask_b32_e32 v106, v216, v106, vcc
	v_cmp_lt_u32_e32 vcc, s82, v0
	v_add_u32_e32 v0, 0x70, v243
	s_nop 0
	v_cndmask_b32_e32 v90, v216, v90, vcc
	v_cmp_lt_u32_e32 vcc, s82, v0
	v_add_u32_e32 v0, 0x50, v243
	s_nop 0
	v_cndmask_b32_e32 v107, v216, v107, vcc
	v_cmp_lt_u32_e32 vcc, s82, v0
	v_add_u32_e32 v0, 0x6b, v243
	s_nop 0
	v_cndmask_b32_e32 v91, v216, v91, vcc
	v_cmp_lt_u32_e32 vcc, s82, v0
	v_add_u32_e32 v0, 0x4b, v243
	s_nop 0
	v_cndmask_b32_e32 v108, v216, v108, vcc
	v_cmp_lt_u32_e32 vcc, s82, v0
	v_add_u32_e32 v0, 0x6a, v243
	s_nop 0
	v_cndmask_b32_e32 v92, v216, v92, vcc
	v_cmp_lt_u32_e32 vcc, s82, v0
	v_add_u32_e32 v0, 0x4a, v243
	s_nop 0
	v_cndmask_b32_e32 v109, v216, v109, vcc
	v_cmp_lt_u32_e32 vcc, s82, v0
	v_add_u32_e32 v0, 0x69, v243
	s_nop 0
	v_cndmask_b32_e32 v93, v216, v93, vcc
	v_cmp_lt_u32_e32 vcc, s82, v0
	v_add_u32_e32 v0, 0x49, v243
	s_nop 0
	v_cndmask_b32_e32 v110, v216, v110, vcc
	v_cmp_lt_u32_e32 vcc, s82, v0
	v_add_u32_e32 v0, 0x68, v243
	s_nop 0
	v_cndmask_b32_e32 v94, v216, v94, vcc
	v_cmp_lt_u32_e32 vcc, s82, v0
	v_add_u32_e32 v0, 0x48, v243
	s_nop 0
	v_cndmask_b32_e32 v111, v216, v111, vcc
	v_cmp_lt_u32_e32 vcc, s82, v0
	v_add_u32_e32 v0, 0x63, v243
	s_nop 0
	v_cndmask_b32_e32 v95, v216, v95, vcc
	v_cmp_lt_u32_e32 vcc, s82, v0
	v_add_u32_e32 v0, 0x43, v243
	s_nop 0
	v_cndmask_b32_e32 v112, v216, v112, vcc
	v_cmp_lt_u32_e32 vcc, s82, v0
	v_add_u32_e32 v0, 0x62, v243
	s_nop 0
	v_cndmask_b32_e32 v96, v216, v96, vcc
	v_cmp_lt_u32_e32 vcc, s82, v0
	v_add_u32_e32 v0, 0x42, v243
	s_nop 0
	v_cndmask_b32_e32 v113, v216, v113, vcc
	v_cmp_lt_u32_e32 vcc, s82, v0
	v_add_u32_e32 v0, 0x61, v243
	s_nop 0
	v_cndmask_b32_e32 v97, v216, v97, vcc
	v_cmp_lt_u32_e32 vcc, s82, v0
	v_add_u32_e32 v0, 0x41, v243
	s_nop 0
	v_cndmask_b32_e32 v114, v216, v114, vcc
	v_cmp_lt_u32_e32 vcc, s82, v0
	v_add_u32_e32 v0, 0x60, v243
	s_nop 0
	v_cndmask_b32_e32 v98, v216, v98, vcc
	v_cmp_lt_u32_e32 vcc, s82, v0
	v_add_u32_e32 v0, 64, v243
	s_nop 0
	v_cndmask_b32_e32 v115, v216, v115, vcc
	v_cmp_lt_u32_e32 vcc, s82, v0
	s_nop 1
	v_cndmask_b32_e32 v99, v216, v99, vcc
; __device__ __forceinline__ void partialSM(f32x16& p0, f32x16& p1, float& m_reg, float& mn, float& alpha) {
;     float pmax = p0[0]; for (int r = 1; r < 16; ++r) pmax = fmaxf(pmax, p0[r]); for (int r = 0; r < 16; ++r) pmax = fmaxf(pmax, p1[r]);
;     { auto rr = __builtin_amdgcn_permlane32_swap(__float_as_uint(pmax), __float_as_uint(pmax), false, false);
;       pmax = fmaxf(__uint_as_float(rr[0]), __uint_as_float(rr[1])); }
;     constexpr float C2 = 1.4426950408889634f * SCALE;
;     if (__builtin_expect(__all((pmax - m_reg) * SCALE <= THR), 1)) { mn = m_reg; alpha = 1.f; }
;     else { mn = fmaxf(m_reg, pmax); alpha = __builtin_amdgcn_exp2f((m_reg - mn) * C2); m_reg = mn; }
;     const float mnL = -mn * C2;
.LBB0_1249:
	v_max_f32_e32 v0, v101, v101
	v_max_f32_e32 v15, v100, v100
	v_max_f32_e32 v0, v15, v0
	v_max3_f32 v0, v0, v102, v103
	v_max3_f32 v0, v0, v104, v105
	v_max3_f32 v0, v0, v106, v107
	v_max3_f32 v0, v0, v108, v109
	v_max3_f32 v0, v0, v110, v111
	v_max3_f32 v0, v0, v112, v113
	v_max3_f32 v0, v0, v114, v115
	v_max3_f32 v0, v0, v84, v85
	v_max3_f32 v0, v0, v86, v87
	v_max3_f32 v0, v0, v88, v89
	v_max3_f32 v0, v0, v90, v91
	v_max3_f32 v0, v0, v92, v93
	v_max3_f32 v0, v0, v94, v95
	v_max3_f32 v0, v0, v96, v97
	v_max3_f32 v0, v0, v98, v99
	v_mov_b32_e32 v15, v0
	s_nop 1
	v_permlane32_swap_b32_e32 v0, v15
	v_max_f32_e32 v15, v15, v15
	v_max_f32_e32 v0, v0, v0
	v_max_f32_e32 v0, v0, v15
	v_sub_f32_e32 v15, v0, v180
	v_mul_f32_e32 v15, 0x3db504f3, v15
	v_cmp_ge_f32_e32 vcc, s83, v15
	v_max_f32_e32 v15, v180, v180
	v_max_f32_e32 v0, v15, v0
	v_sub_f32_e32 v15, v180, v0
	v_mul_f32_e32 v15, 0x3e0293ee, v15
	v_exp_f32_e32 v15, v15
	s_cmp_eq_u64 vcc, exec
	s_cselect_b64 s[4:5], -1, 0
	s_barrier
	s_waitcnt vmcnt(0)
	v_cndmask_b32_e64 v15, v15, 1.0, s[4:5]
	v_cmp_gt_f32_e32 vcc, 1.0, v15
	s_waitcnt vmcnt(3)
	ds_write_b128 v237, v[2:5]
	s_waitcnt vmcnt(2)
	ds_write_b128 v238, v[6:9]
	ds_write_b32 v242, v246
	s_waitcnt vmcnt(1)
	ds_write_b128 v222, v[10:13] offset:32768
	s_waitcnt vmcnt(0)
	ds_write_b128 v222, v[210:213] offset:40960
	s_cbranch_vccz .LBB0_1253
	s_and_saveexec_b64 s[28:29], s[2:3]
	ds_write_b32 v226, v15 offset:128
	s_or_b64 exec, exec, s[28:29]
	s_waitcnt lgkmcnt(0)
	ds_read_b128 v[80:83], v225 offset:224
	ds_read_b128 v[116:119], v225 offset:192
	ds_read_b128 v[120:123], v225 offset:160
	ds_read_b128 v[124:127], v225 offset:128
	s_waitcnt lgkmcnt(3)
	v_pk_mul_f32 v[78:79], v[78:79], v[82:83]
	s_waitcnt lgkmcnt(2)
	v_pk_mul_f32 v[74:75], v[74:75], v[118:119]
	s_waitcnt lgkmcnt(1)
	v_pk_mul_f32 v[70:71], v[70:71], v[122:123]
	s_waitcnt lgkmcnt(0)
	v_pk_mul_f32 v[66:67], v[66:67], v[126:127]
	v_pk_mul_f32 v[76:77], v[76:77], v[80:81]
	v_pk_mul_f32 v[72:73], v[72:73], v[116:117]
	v_pk_mul_f32 v[68:69], v[68:69], v[120:121]
	v_pk_mul_f32 v[64:65], v[64:65], v[124:125]
	v_pk_mul_f32 v[62:63], v[62:63], v[82:83]
	v_pk_mul_f32 v[58:59], v[58:59], v[118:119]
	v_pk_mul_f32 v[54:55], v[54:55], v[122:123]
	v_pk_mul_f32 v[50:51], v[50:51], v[126:127]
	v_pk_mul_f32 v[60:61], v[60:61], v[80:81]
	v_pk_mul_f32 v[56:57], v[56:57], v[116:117]
	v_pk_mul_f32 v[52:53], v[52:53], v[120:121]
	v_pk_mul_f32 v[48:49], v[48:49], v[124:125]
	v_pk_mul_f32 v[46:47], v[46:47], v[82:83]
	v_pk_mul_f32 v[42:43], v[42:43], v[118:119]
	v_pk_mul_f32 v[38:39], v[38:39], v[122:123]
	v_pk_mul_f32 v[34:35], v[34:35], v[126:127]
	v_pk_mul_f32 v[44:45], v[44:45], v[80:81]
	v_pk_mul_f32 v[40:41], v[40:41], v[116:117]
	v_pk_mul_f32 v[36:37], v[36:37], v[120:121]
	v_pk_mul_f32 v[32:33], v[32:33], v[124:125]
	v_pk_mul_f32 v[30:31], v[30:31], v[82:83]
	v_pk_mul_f32 v[26:27], v[26:27], v[118:119]
	v_pk_mul_f32 v[22:23], v[22:23], v[122:123]
	v_pk_mul_f32 v[18:19], v[18:19], v[126:127]
	v_pk_mul_f32 v[28:29], v[28:29], v[80:81]
	v_pk_mul_f32 v[24:25], v[24:25], v[116:117]
	v_pk_mul_f32 v[20:21], v[20:21], v[120:121]
	v_pk_mul_f32 v[16:17], v[16:17], v[124:125]
